# ADIFF fast path: 4 fragment buffers round-robin (3-pair LDS lead), barrier moved mid-PV
# baseline (speedup 1.0000x reference)
; __device__ __forceinline__ void diff_attn_phase(const Params& p, LAS unsigned char* lds) {
;     ...
;         auto issue = [&](int ch, int stg) {
;             const char* kg = (const char*)(kp + (tokb + 64 * ch) * ld); const char* vg = (const char*)(vp + (tokb + 64 * ch) * ld);
;             LAS unsigned char* sb = lds + stg * STG;
; #pragma unroll
;             for (int i = 0; i < 2; ++i) { unsigned o = doff[i]; asm volatile("" : "+v"(o));
;                 __builtin_amdgcn_global_load_lds((const void*)(kg + o), (LAS void*)(sb + dlds[i]), 16, 0, 0);
;                 __builtin_amdgcn_global_load_lds((const void*)(vg + o), (LAS void*)(sb + 16384 + dlds[i]), 16, 0, 0); }
;         };
;         issue(0, 0); issue(1, 1);
;         int s_cur = 0, s_nn = 2;
;         for (int ch = 0; ch < NCH; ++ch) {
;             if (ch + 1 < NCH) asm volatile("s_waitcnt vmcnt(4)" ::: "memory"); else asm volatile("s_waitcnt vmcnt(0)" ::: "memory");
;             __builtin_amdgcn_s_barrier(); asm volatile("" ::: "memory");
;             if (ch + 2 < NCH) issue(ch + 2, s_nn);
;             const LAS unsigned char* Ksb = lds + s_cur * STG; const LAS unsigned char* Vsb = Ksb + 16384;
;             s_nn = s_cur; s_cur = (s_cur == 2) ? 0 : s_cur + 1;
; #pragma clang loop unroll(disable)
;             for (int u = 0; u < 2; ++u) {
;                 const LAS unsigned char* Ku = Ksb + u * 8192; const LAS unsigned char* Vu = Vsb + u * 8192;
;                 int kxl = kx, vb0l = vb0, vb1l = vb1; asm volatile("" : "+v"(kxl), "+v"(vb0l), "+v"(vb1l));
;                 bf16x8 kf[4];
; #pragma unroll
;                 for (int ks = 0; ks < 4; ++ks) kf[ks] = *(const LAS bf16x8*)(Ku + kbase + (kxl ^ (32 * ks)));
;                 bf16x8 P[2][2];
; #pragma unroll
;                 for (int r = 0; r < 2; ++r) {
;                     f32x16 S;
; #pragma unroll
;                     for (int i = 0; i < 16; ++i) S[i] = 0.f;
; #pragma unroll
;                     for (int ks = 0; ks < 4; ++ks) S = __builtin_amdgcn_mfma_f32_32x32x16_bf16(kf[ks], qf[r][ks], S, 0, 0, 0);
;                     S = __builtin_amdgcn_mfma_f32_32x32x16_bf16(kone, qm[r], S, 0, 0, 0);
; #pragma unroll
;                     for (int i = 0; i < 16; ++i) S[i] = __builtin_amdgcn_exp2f(S[i]);
;                     l[r] += sum16(S);
;                     P[r][0] = pack8(S, 0); P[r][1] = pack8(S, 8);
.Lfa_entry:
	s_waitcnt lgkmcnt(0)
	v_readfirstlane_b32 s34, v242
	s_movk_i32 s47, 0x60
	s_waitcnt vmcnt(4)
	s_barrier
	s_add_i32 s2, s29, 2
	s_lshl_b32 s10, s2, 6
	s_add_u32 s10, s26, s10
	s_addc_u32 s11, s27, 0
	s_lshl_b64 s[10:11], s[10:11], 13
	s_add_u32 s42, s25, s10
	s_addc_u32 s43, s28, s11
	s_add_u32 s10, s22, s10
	s_addc_u32 s11, s23, s11
	s_and_b32 s2, s2, 3
	s_lshl_b32 s2, s2, 15
	s_add_i32 s2, s2, s34
	s_mov_b32 m0, s2
	s_add_i32 s35, s2, 0x4000
	global_load_lds_dwordx4 v241, s[42:43]
	s_mov_b32 m0, s35
	s_add_i32 s35, s2, 0x2000
	global_load_lds_dwordx4 v241, s[10:11]
	s_mov_b32 m0, s35
	s_add_i32 s35, s2, 0x6000
	global_load_lds_dwordx4 v243, s[42:43]
	s_mov_b32 m0, s35
	s_nop 0
	global_load_lds_dwordx4 v243, s[10:11]
	v_mov_b32_e32 v1, v245
	v_mov_b32_e32 v234, v247
	v_mov_b32_e32 v235, v248
	v_xor_b32_e32 v237, 64, v247
	v_xor_b32_e32 v236, 64, v248
	v_xor_b32_e32 v238, 0x80, v247
	v_xor_b32_e32 v239, 0x80, v248
	v_xor_b32_e32 v250, 0xc0, v247
	v_xor_b32_e32 v251, 0xc0, v248
	v_add_u32_e32 v198, v246, v1
	ds_read_b128 v[198:201], v198
	v_xad_u32 v202, v246, 32, v1
	ds_read_b128 v[202:205], v202
	v_xad_u32 v208, v246, 64, v1
	ds_read_b128 v[208:211], v208
	v_xad_u32 v230, v246, s47, v1
	ds_read_b128 v[230:233], v230
	s_waitcnt lgkmcnt(3)
	v_mfma_f32_32x32x16_bf16 v[146:161], v[198:201], v[166:169], 0
	v_mfma_f32_32x32x16_bf16 v[130:145], v[198:201], v[182:185], 0
	v_add_u32_e32 v198, v246, v1
	ds_read_b128 v[198:201], v198 offset:8192
	s_waitcnt lgkmcnt(3)
	v_mfma_f32_32x32x16_bf16 v[146:161], v[202:205], v[170:173], v[146:161]
	v_mfma_f32_32x32x16_bf16 v[130:145], v[202:205], v[186:189], v[130:145]
	v_xad_u32 v202, v246, 32, v1
	ds_read_b128 v[202:205], v202 offset:8192
	s_waitcnt lgkmcnt(3)
	v_mfma_f32_32x32x16_bf16 v[146:161], v[208:211], v[174:177], v[146:161]
	v_mfma_f32_32x32x16_bf16 v[130:145], v[208:211], v[190:193], v[130:145]
	v_xad_u32 v208, v246, 64, v1
	ds_read_b128 v[208:211], v208 offset:8192
	s_waitcnt lgkmcnt(3)
	v_mfma_f32_32x32x16_bf16 v[146:161], v[230:233], v[178:181], v[146:161]
	v_mfma_f32_32x32x16_bf16 v[130:145], v[230:233], v[194:197], v[130:145]
	v_xad_u32 v230, v246, s47, v1
	ds_read_b128 v[230:233], v230 offset:8192
	s_nop 7
	s_nop 1
	v_exp_f32_e32 v146, v146
	v_exp_f32_e32 v130, v130
	v_exp_f32_e32 v147, v147
	v_exp_f32_e32 v131, v131
	v_add_f32_e32 v213, v213, v146
	v_add_f32_e32 v212, v212, v130
	v_add_f32_e32 v213, v213, v147
	v_add_f32_e32 v212, v212, v131
	v_exp_f32_e32 v148, v148
	v_exp_f32_e32 v132, v132
	v_exp_f32_e32 v149, v149
	v_exp_f32_e32 v133, v133
	v_add_f32_e32 v213, v213, v148
	v_add_f32_e32 v212, v212, v132
	v_add_f32_e32 v213, v213, v149
	v_add_f32_e32 v212, v212, v133
	v_exp_f32_e32 v150, v150
	v_exp_f32_e32 v134, v134
	v_exp_f32_e32 v151, v151
	v_exp_f32_e32 v135, v135
	v_add_f32_e32 v213, v213, v150
	v_add_f32_e32 v212, v212, v134
	v_add_f32_e32 v213, v213, v151
	v_add_f32_e32 v212, v212, v135
	v_exp_f32_e32 v152, v152
	v_exp_f32_e32 v136, v136
	v_exp_f32_e32 v153, v153
	v_exp_f32_e32 v137, v137
	v_add_f32_e32 v213, v213, v152
	v_add_f32_e32 v212, v212, v136
	v_add_f32_e32 v213, v213, v153
	v_add_f32_e32 v212, v212, v137
	v_cvt_pk_bf16_f32 v214, v146, v147
	v_cvt_pk_bf16_f32 v218, v130, v131
	v_cvt_pk_bf16_f32 v215, v148, v149
	v_cvt_pk_bf16_f32 v219, v132, v133
	v_cvt_pk_bf16_f32 v216, v150, v151
	v_cvt_pk_bf16_f32 v220, v134, v135
	v_cvt_pk_bf16_f32 v217, v152, v153
	v_cvt_pk_bf16_f32 v221, v136, v137
	v_exp_f32_e32 v154, v154
	v_exp_f32_e32 v138, v138
	v_exp_f32_e32 v155, v155
	v_exp_f32_e32 v139, v139
	v_add_f32_e32 v213, v213, v154
	v_add_f32_e32 v212, v212, v138
	v_add_f32_e32 v213, v213, v155
	v_add_f32_e32 v212, v212, v139
	v_exp_f32_e32 v156, v156
	v_exp_f32_e32 v140, v140
	v_exp_f32_e32 v157, v157
	v_exp_f32_e32 v141, v141
	v_add_f32_e32 v213, v213, v156
	v_add_f32_e32 v212, v212, v140
	v_add_f32_e32 v213, v213, v157
	v_add_f32_e32 v212, v212, v141
	v_exp_f32_e32 v158, v158
	v_exp_f32_e32 v142, v142
	v_exp_f32_e32 v159, v159
	v_exp_f32_e32 v143, v143
	v_add_f32_e32 v213, v213, v158
	v_add_f32_e32 v212, v212, v142
	v_add_f32_e32 v213, v213, v159
	v_add_f32_e32 v212, v212, v143
	v_exp_f32_e32 v160, v160
	v_exp_f32_e32 v144, v144
	v_exp_f32_e32 v161, v161
	v_exp_f32_e32 v145, v145
	v_add_f32_e32 v213, v213, v160
	v_add_f32_e32 v212, v212, v144
	v_add_f32_e32 v213, v213, v161
	v_add_f32_e32 v212, v212, v145
	v_cvt_pk_bf16_f32 v222, v154, v155
	v_cvt_pk_bf16_f32 v226, v138, v139
	v_cvt_pk_bf16_f32 v223, v156, v157
	v_cvt_pk_bf16_f32 v227, v140, v141
	v_cvt_pk_bf16_f32 v224, v158, v159
	v_cvt_pk_bf16_f32 v228, v142, v143
	v_cvt_pk_bf16_f32 v225, v160, v161
	v_cvt_pk_bf16_f32 v229, v144, v145
; #define LAS __attribute__((address_space(3)))
; __device__ __forceinline__ void diff_attn_phase(const Params& p, LAS unsigned char* lds) {
;     ...
;             for (int u = 0; u < 2; ++u) {
;                 const LAS unsigned char* Ku = Ksb + u * 8192; const LAS unsigned char* Vu = Vsb + u * 8192;
;                 int kxl = kx, vb0l = vb0, vb1l = vb1; asm volatile("" : "+v"(kxl), "+v"(vb0l), "+v"(vb1l));
;                 bf16x8 kf[4];
; #pragma unroll
;                 for (int ks = 0; ks < 4; ++ks) kf[ks] = *(const LAS bf16x8*)(Ku + kbase + (kxl ^ (32 * ks)));
;                 bf16x8 P[2][2];
; #pragma unroll
;                 for (int r = 0; r < 2; ++r) {
;                     f32x16 S;
; #pragma unroll
;                     for (int i = 0; i < 16; ++i) S[i] = 0.f;
; #pragma unroll
;                     for (int ks = 0; ks < 4; ++ks) S = __builtin_amdgcn_mfma_f32_32x32x16_bf16(kf[ks], qf[r][ks], S, 0, 0, 0);
;                     S = __builtin_amdgcn_mfma_f32_32x32x16_bf16(kone, qm[r], S, 0, 0, 0);
; #pragma unroll
;                     for (int i = 0; i < 16; ++i) S[i] = __builtin_amdgcn_exp2f(S[i]);
;                     l[r] += sum16(S);
;                     P[r][0] = pack8(S, 0); P[r][1] = pack8(S, 8);
;                 }
; #pragma unroll
;                 for (int t = 0; t < 4; ++t) {
;                     const LAS unsigned char* a0 = Vu + (vb0l ^ (64 * t)); const LAS unsigned char* a1 = Vu + (vb1l ^ (64 * t));
;                     const bf16x8 v0 = tr_pair(a0, a1), v1 = tr_pair(a0 + 4096, a1 + 4096);
;                     O[0][t] = __builtin_amdgcn_mfma_f32_32x32x16_bf16(v0, P[0][0], O[0][t], 0, 0, 0);
;                     O[1][t] = __builtin_amdgcn_mfma_f32_32x32x16_bf16(v0, P[1][0], O[1][t], 0, 0, 0);
;                     O[0][t] = __builtin_amdgcn_mfma_f32_32x32x16_bf16(v1, P[0][1], O[0][t], 0, 0, 0);
;                     O[1][t] = __builtin_amdgcn_mfma_f32_32x32x16_bf16(v1, P[1][1], O[1][t], 0, 0, 0);
;                 }
.Lfb_loop:
	s_waitcnt lgkmcnt(3)
	v_mfma_f32_32x32x16_bf16 v[146:161], v[198:201], v[166:169], 0
	v_mfma_f32_32x32x16_bf16 v[130:145], v[198:201], v[182:185], 0
	ds_read_b64_tr_b16 v[198:199], v234 offset:16384
	ds_read_b64_tr_b16 v[200:201], v235 offset:16384
	s_waitcnt lgkmcnt(4)
	v_mfma_f32_32x32x16_bf16 v[146:161], v[202:205], v[170:173], v[146:161]
	v_mfma_f32_32x32x16_bf16 v[130:145], v[202:205], v[186:189], v[130:145]
	ds_read_b64_tr_b16 v[202:203], v237 offset:16384
	ds_read_b64_tr_b16 v[204:205], v236 offset:16384
	s_waitcnt lgkmcnt(5)
	v_mfma_f32_32x32x16_bf16 v[146:161], v[208:211], v[174:177], v[146:161]
	v_mfma_f32_32x32x16_bf16 v[130:145], v[208:211], v[190:193], v[130:145]
	ds_read_b64_tr_b16 v[208:209], v238 offset:16384
	ds_read_b64_tr_b16 v[210:211], v239 offset:16384
	s_waitcnt lgkmcnt(6)
	v_mfma_f32_32x32x16_bf16 v[146:161], v[230:233], v[178:181], v[146:161]
	v_mfma_f32_32x32x16_bf16 v[130:145], v[230:233], v[194:197], v[130:145]
	ds_read_b64_tr_b16 v[230:231], v250 offset:16384
	ds_read_b64_tr_b16 v[232:233], v251 offset:16384
	s_waitcnt lgkmcnt(6)
	v_mfma_f32_32x32x16_bf16 v[114:129], v[198:201], v[214:217], v[114:129]
	v_mfma_f32_32x32x16_bf16 v[50:65], v[198:201], v[218:221], v[50:65]
	ds_read_b64_tr_b16 v[198:199], v234 offset:20480
	ds_read_b64_tr_b16 v[200:201], v235 offset:20480
	s_waitcnt lgkmcnt(6)
	v_mfma_f32_32x32x16_bf16 v[98:113], v[202:205], v[214:217], v[98:113]
	v_mfma_f32_32x32x16_bf16 v[34:49], v[202:205], v[218:221], v[34:49]
	ds_read_b64_tr_b16 v[202:203], v237 offset:20480
	ds_read_b64_tr_b16 v[204:205], v236 offset:20480
	v_exp_f32_e32 v146, v146
	v_exp_f32_e32 v130, v130
	v_exp_f32_e32 v147, v147
	v_exp_f32_e32 v131, v131
	v_add_f32_e32 v213, v213, v146
	v_add_f32_e32 v212, v212, v130
	s_waitcnt lgkmcnt(6)
	v_mfma_f32_32x32x16_bf16 v[82:97], v[208:211], v[214:217], v[82:97]
	v_add_f32_e32 v213, v213, v147
	v_add_f32_e32 v212, v212, v131
	v_exp_f32_e32 v148, v148
	v_exp_f32_e32 v132, v132
	v_exp_f32_e32 v149, v149
	v_exp_f32_e32 v133, v133
	v_mfma_f32_32x32x16_bf16 v[18:33], v[208:211], v[218:221], v[18:33]
	ds_read_b64_tr_b16 v[208:209], v238 offset:20480
	ds_read_b64_tr_b16 v[210:211], v239 offset:20480
	v_add_f32_e32 v213, v213, v148
	v_add_f32_e32 v212, v212, v132
	v_add_f32_e32 v213, v213, v149
	v_add_f32_e32 v212, v212, v133
	v_exp_f32_e32 v150, v150
	v_exp_f32_e32 v134, v134
	s_waitcnt lgkmcnt(6)
	v_mfma_f32_32x32x16_bf16 v[66:81], v[230:233], v[214:217], v[66:81]
	v_exp_f32_e32 v151, v151
	v_exp_f32_e32 v135, v135
	v_add_f32_e32 v213, v213, v150
	v_add_f32_e32 v212, v212, v134
	v_add_f32_e32 v213, v213, v151
	v_add_f32_e32 v212, v212, v135
	v_mfma_f32_32x32x16_bf16 v[2:17], v[230:233], v[218:221], v[2:17]
	ds_read_b64_tr_b16 v[230:231], v250 offset:20480
	ds_read_b64_tr_b16 v[232:233], v251 offset:20480
	v_exp_f32_e32 v152, v152
	v_exp_f32_e32 v136, v136
	v_exp_f32_e32 v153, v153
	v_exp_f32_e32 v137, v137
	v_add_f32_e32 v213, v213, v152
	v_add_f32_e32 v212, v212, v136
	s_cmpk_eq_u32 s29, 0x7f
	s_cbranch_scc1 .Lfb_last0
	s_cmpk_eq_u32 s29, 0x7e
	s_cbranch_scc1 .Lfb_w0
	s_waitcnt vmcnt(4)
	s_branch .Lfb_w1

; #define LAS __attribute__((address_space(3)))
; __device__ __forceinline__ void diff_attn_phase(const Params& p, LAS unsigned char* lds) {
;     ...
;         for (int ch = 0; ch < NCH; ++ch) {
;             if (ch + 1 < NCH) asm volatile("s_waitcnt vmcnt(4)" ::: "memory"); else asm volatile("s_waitcnt vmcnt(0)" ::: "memory");
;             __builtin_amdgcn_s_barrier(); asm volatile("" ::: "memory");
;             if (ch + 2 < NCH) issue(ch + 2, s_nn);
;             const LAS unsigned char* Ksb = lds + s_cur * STG; const LAS unsigned char* Vsb = Ksb + 16384;
;             s_nn = s_cur; s_cur = (s_cur == 2) ? 0 : s_cur + 1;
; #pragma clang loop unroll(disable)
;             for (int u = 0; u < 2; ++u) {
;                 const LAS unsigned char* Ku = Ksb + u * 8192; const LAS unsigned char* Vu = Vsb + u * 8192;
;                 int kxl = kx, vb0l = vb0, vb1l = vb1; asm volatile("" : "+v"(kxl), "+v"(vb0l), "+v"(vb1l));
;                 bf16x8 kf[4];
; #pragma unroll
;                 for (int ks = 0; ks < 4; ++ks) kf[ks] = *(const LAS bf16x8*)(Ku + kbase + (kxl ^ (32 * ks)));
;                 bf16x8 P[2][2];
; #pragma unroll
;                 for (int r = 0; r < 2; ++r) {
;                     f32x16 S;
; #pragma unroll
;                     for (int i = 0; i < 16; ++i) S[i] = 0.f;
; #pragma unroll
;                     for (int ks = 0; ks < 4; ++ks) S = __builtin_amdgcn_mfma_f32_32x32x16_bf16(kf[ks], qf[r][ks], S, 0, 0, 0);
;                     S = __builtin_amdgcn_mfma_f32_32x32x16_bf16(kone, qm[r], S, 0, 0, 0);
; #pragma unroll
;                     for (int i = 0; i < 16; ++i) S[i] = __builtin_amdgcn_exp2f(S[i]);
;                     l[r] += sum16(S);
;                     P[r][0] = pack8(S, 0); P[r][1] = pack8(S, 8);
;                 }
; #pragma unroll
;                 for (int t = 0; t < 4; ++t) {
;                     const LAS unsigned char* a0 = Vu + (vb0l ^ (64 * t)); const LAS unsigned char* a1 = Vu + (vb1l ^ (64 * t));
;                     const bf16x8 v0 = tr_pair(a0, a1), v1 = tr_pair(a0 + 4096, a1 + 4096);
;                     O[0][t] = __builtin_amdgcn_mfma_f32_32x32x16_bf16(v0, P[0][0], O[0][t], 0, 0, 0);
;                     O[1][t] = __builtin_amdgcn_mfma_f32_32x32x16_bf16(v0, P[1][0], O[1][t], 0, 0, 0);
;                     O[0][t] = __builtin_amdgcn_mfma_f32_32x32x16_bf16(v1, P[0][1], O[0][t], 0, 0, 0);
.Lfb_nodma:
	s_add_i32 s2, s29, 1
	s_and_b32 s2, s2, 3
	s_mov_b32 s37, 0x8000
	s_cmp_eq_u32 s2, 0
	s_cselect_b32 s37, 0xfffe8000, s37
	v_add_u32_e32 v1, s37, v1
	s_waitcnt lgkmcnt(6)
	v_mfma_f32_32x32x16_bf16 v[114:129], v[198:201], v[222:225], v[114:129]
	v_add_f32_e32 v213, v213, v153
	v_add_f32_e32 v212, v212, v137
	v_cvt_pk_bf16_f32 v214, v146, v147
	v_cvt_pk_bf16_f32 v218, v130, v131
	v_cvt_pk_bf16_f32 v215, v148, v149
	v_cvt_pk_bf16_f32 v219, v132, v133
	v_cvt_pk_bf16_f32 v216, v150, v151
	v_cvt_pk_bf16_f32 v220, v134, v135
	v_cvt_pk_bf16_f32 v217, v152, v153
	v_cvt_pk_bf16_f32 v221, v136, v137
	v_mfma_f32_32x32x16_bf16 v[50:65], v[198:201], v[226:229], v[50:65]
	v_add_u32_e32 v198, v246, v1
	ds_read_b128 v[198:201], v198
	v_exp_f32_e32 v154, v154
	v_exp_f32_e32 v138, v138
	v_exp_f32_e32 v155, v155
	v_exp_f32_e32 v139, v139
	v_add_f32_e32 v213, v213, v154
	s_waitcnt lgkmcnt(5)
	v_mfma_f32_32x32x16_bf16 v[98:113], v[202:205], v[222:225], v[98:113]
	v_add_f32_e32 v212, v212, v138
	v_add_f32_e32 v213, v213, v155
	v_add_f32_e32 v212, v212, v139
	v_exp_f32_e32 v156, v156
	v_exp_f32_e32 v140, v140
	v_mfma_f32_32x32x16_bf16 v[34:49], v[202:205], v[226:229], v[34:49]
	v_xad_u32 v202, v246, 32, v1
	ds_read_b128 v[202:205], v202
	v_exp_f32_e32 v157, v157
	v_exp_f32_e32 v141, v141
	v_add_f32_e32 v213, v213, v156
	v_add_f32_e32 v212, v212, v140
	v_add_f32_e32 v213, v213, v157
	s_waitcnt lgkmcnt(4)
	v_mfma_f32_32x32x16_bf16 v[82:97], v[208:211], v[222:225], v[82:97]
	v_add_f32_e32 v212, v212, v141
	v_exp_f32_e32 v158, v158
	v_exp_f32_e32 v142, v142
	v_exp_f32_e32 v159, v159
	v_exp_f32_e32 v143, v143
	v_mfma_f32_32x32x16_bf16 v[18:33], v[208:211], v[226:229], v[18:33]
	v_xad_u32 v208, v246, 64, v1
	ds_read_b128 v[208:211], v208
	v_add_f32_e32 v213, v213, v158
	v_add_f32_e32 v212, v212, v142
	v_add_f32_e32 v213, v213, v159
	v_add_f32_e32 v212, v212, v143
	s_waitcnt lgkmcnt(3)
	v_mfma_f32_32x32x16_bf16 v[66:81], v[230:233], v[222:225], v[66:81]
	v_exp_f32_e32 v160, v160
	v_exp_f32_e32 v144, v144
	v_exp_f32_e32 v161, v161
	v_exp_f32_e32 v145, v145
	v_mfma_f32_32x32x16_bf16 v[2:17], v[230:233], v[226:229], v[2:17]
	v_xad_u32 v230, v246, s47, v1
	ds_read_b128 v[230:233], v230
	v_add_f32_e32 v213, v213, v160
	v_add_f32_e32 v212, v212, v144
	v_add_f32_e32 v213, v213, v161
	v_add_f32_e32 v212, v212, v145
	v_cvt_pk_bf16_f32 v222, v154, v155
	v_cvt_pk_bf16_f32 v226, v138, v139
	v_cvt_pk_bf16_f32 v223, v156, v157
	v_cvt_pk_bf16_f32 v227, v140, v141
	v_cvt_pk_bf16_f32 v224, v158, v159
	v_cvt_pk_bf16_f32 v228, v142, v143
	v_cvt_pk_bf16_f32 v225, v160, v161
	v_cvt_pk_bf16_f32 v229, v144, v145
	s_waitcnt lgkmcnt(3)
	v_mfma_f32_32x32x16_bf16 v[146:161], v[198:201], v[166:169], 0
	v_mfma_f32_32x32x16_bf16 v[130:145], v[198:201], v[182:185], 0
	ds_read_b64_tr_b16 v[198:199], v234 offset:24576
	ds_read_b64_tr_b16 v[200:201], v235 offset:24576
	s_waitcnt lgkmcnt(4)
	v_mfma_f32_32x32x16_bf16 v[146:161], v[202:205], v[170:173], v[146:161]
	v_mfma_f32_32x32x16_bf16 v[130:145], v[202:205], v[186:189], v[130:145]
	ds_read_b64_tr_b16 v[202:203], v237 offset:24576
	ds_read_b64_tr_b16 v[204:205], v236 offset:24576
	s_waitcnt lgkmcnt(5)
	v_mfma_f32_32x32x16_bf16 v[146:161], v[208:211], v[174:177], v[146:161]
	v_mfma_f32_32x32x16_bf16 v[130:145], v[208:211], v[190:193], v[130:145]
	ds_read_b64_tr_b16 v[208:209], v238 offset:24576
	ds_read_b64_tr_b16 v[210:211], v239 offset:24576
	s_waitcnt lgkmcnt(6)
	v_mfma_f32_32x32x16_bf16 v[146:161], v[230:233], v[178:181], v[146:161]
	v_mfma_f32_32x32x16_bf16 v[130:145], v[230:233], v[194:197], v[130:145]
	ds_read_b64_tr_b16 v[230:231], v250 offset:24576
	ds_read_b64_tr_b16 v[232:233], v251 offset:24576
	s_waitcnt lgkmcnt(6)
	v_mfma_f32_32x32x16_bf16 v[114:129], v[198:201], v[214:217], v[114:129]
	v_mfma_f32_32x32x16_bf16 v[50:65], v[198:201], v[218:221], v[50:65]
	ds_read_b64_tr_b16 v[198:199], v234 offset:28672
	ds_read_b64_tr_b16 v[200:201], v235 offset:28672
	s_waitcnt lgkmcnt(6)
	v_mfma_f32_32x32x16_bf16 v[98:113], v[202:205], v[214:217], v[98:113]
	v_mfma_f32_32x32x16_bf16 v[34:49], v[202:205], v[218:221], v[34:49]
	ds_read_b64_tr_b16 v[202:203], v237 offset:28672
	ds_read_b64_tr_b16 v[204:205], v236 offset:28672
	v_exp_f32_e32 v146, v146
	v_exp_f32_e32 v130, v130
	v_exp_f32_e32 v147, v147
	v_exp_f32_e32 v131, v131
	v_add_f32_e32 v213, v213, v146
	v_add_f32_e32 v212, v212, v130
	s_waitcnt lgkmcnt(6)
	v_mfma_f32_32x32x16_bf16 v[82:97], v[208:211], v[214:217], v[82:97]
	v_add_f32_e32 v213, v213, v147
	v_add_f32_e32 v212, v212, v131
	v_exp_f32_e32 v148, v148
	v_exp_f32_e32 v132, v132
	v_exp_f32_e32 v149, v149
	v_exp_f32_e32 v133, v133
	v_mfma_f32_32x32x16_bf16 v[18:33], v[208:211], v[218:221], v[18:33]
	ds_read_b64_tr_b16 v[208:209], v238 offset:28672
	ds_read_b64_tr_b16 v[210:211], v239 offset:28672
	v_add_f32_e32 v213, v213, v148
	v_add_f32_e32 v212, v212, v132
	v_add_f32_e32 v213, v213, v149
	v_add_f32_e32 v212, v212, v133
	v_exp_f32_e32 v150, v150
	v_exp_f32_e32 v134, v134
	s_waitcnt lgkmcnt(6)
	v_mfma_f32_32x32x16_bf16 v[66:81], v[230:233], v[214:217], v[66:81]
	v_exp_f32_e32 v151, v151
	v_exp_f32_e32 v135, v135
	v_add_f32_e32 v213, v213, v150
	v_add_f32_e32 v212, v212, v134
	v_add_f32_e32 v213, v213, v151
	v_add_f32_e32 v212, v212, v135
	v_mfma_f32_32x32x16_bf16 v[2:17], v[230:233], v[218:221], v[2:17]
	ds_read_b64_tr_b16 v[230:231], v250 offset:28672
	ds_read_b64_tr_b16 v[232:233], v251 offset:28672
	v_exp_f32_e32 v152, v152
	v_exp_f32_e32 v136, v136
	v_exp_f32_e32 v153, v153
	v_exp_f32_e32 v137, v137
	v_add_f32_e32 v213, v213, v152
	v_add_f32_e32 v212, v212, v136
	v_add_u32_e32 v234, s37, v234
	v_add_u32_e32 v235, s37, v235
	v_add_u32_e32 v237, s37, v237
	v_add_u32_e32 v236, s37, v236
	v_add_u32_e32 v238, s37, v238
	v_add_u32_e32 v239, s37, v239
	v_add_u32_e32 v250, s37, v250
	v_add_u32_e32 v251, s37, v251
	s_waitcnt lgkmcnt(6)
; #define LAS __attribute__((address_space(3)))
; __device__ __forceinline__ void diff_attn_phase(const Params& p, LAS unsigned char* lds) {
;     ...
;             for (int u = 0; u < 2; ++u) {
;                 const LAS unsigned char* Ku = Ksb + u * 8192; const LAS unsigned char* Vu = Vsb + u * 8192;
;                 int kxl = kx, vb0l = vb0, vb1l = vb1; asm volatile("" : "+v"(kxl), "+v"(vb0l), "+v"(vb1l));
;                 bf16x8 kf[4];
; #pragma unroll
;                 for (int ks = 0; ks < 4; ++ks) kf[ks] = *(const LAS bf16x8*)(Ku + kbase + (kxl ^ (32 * ks)));
;                 bf16x8 P[2][2];
; #pragma unroll
;                 for (int r = 0; r < 2; ++r) {
;                     f32x16 S;
; #pragma unroll
;                     for (int i = 0; i < 16; ++i) S[i] = 0.f;
; #pragma unroll
;                     for (int ks = 0; ks < 4; ++ks) S = __builtin_amdgcn_mfma_f32_32x32x16_bf16(kf[ks], qf[r][ks], S, 0, 0, 0);
;                     S = __builtin_amdgcn_mfma_f32_32x32x16_bf16(kone, qm[r], S, 0, 0, 0);
; #pragma unroll
;                     for (int i = 0; i < 16; ++i) S[i] = __builtin_amdgcn_exp2f(S[i]);
;                     l[r] += sum16(S);
;                     P[r][0] = pack8(S, 0); P[r][1] = pack8(S, 8);
;                 }
; #pragma unroll
;                 for (int t = 0; t < 4; ++t) {
;                     const LAS unsigned char* a0 = Vu + (vb0l ^ (64 * t)); const LAS unsigned char* a1 = Vu + (vb1l ^ (64 * t));
;                     const bf16x8 v0 = tr_pair(a0, a1), v1 = tr_pair(a0 + 4096, a1 + 4096);
;                     O[0][t] = __builtin_amdgcn_mfma_f32_32x32x16_bf16(v0, P[0][0], O[0][t], 0, 0, 0);
;                     O[1][t] = __builtin_amdgcn_mfma_f32_32x32x16_bf16(v0, P[1][0], O[1][t], 0, 0, 0);
;                     O[0][t] = __builtin_amdgcn_mfma_f32_32x32x16_bf16(v1, P[0][1], O[0][t], 0, 0, 0);
;                     O[1][t] = __builtin_amdgcn_mfma_f32_32x32x16_bf16(v1, P[1][1], O[1][t], 0, 0, 0);
;                 }
	v_mfma_f32_32x32x16_bf16 v[114:129], v[198:201], v[222:225], v[114:129]
	v_add_f32_e32 v213, v213, v153
	v_add_f32_e32 v212, v212, v137
	v_cvt_pk_bf16_f32 v214, v146, v147
	v_cvt_pk_bf16_f32 v218, v130, v131
	v_cvt_pk_bf16_f32 v215, v148, v149
	v_cvt_pk_bf16_f32 v219, v132, v133
	v_cvt_pk_bf16_f32 v216, v150, v151
	v_cvt_pk_bf16_f32 v220, v134, v135
	v_cvt_pk_bf16_f32 v217, v152, v153
	v_cvt_pk_bf16_f32 v221, v136, v137
	v_mfma_f32_32x32x16_bf16 v[50:65], v[198:201], v[226:229], v[50:65]
	v_add_u32_e32 v198, v246, v1
	ds_read_b128 v[198:201], v198 offset:8192
	v_exp_f32_e32 v154, v154
	v_exp_f32_e32 v138, v138
	v_exp_f32_e32 v155, v155
	v_exp_f32_e32 v139, v139
	v_add_f32_e32 v213, v213, v154
	s_waitcnt lgkmcnt(5)
	v_mfma_f32_32x32x16_bf16 v[98:113], v[202:205], v[222:225], v[98:113]
	v_add_f32_e32 v212, v212, v138
	v_add_f32_e32 v213, v213, v155
	v_add_f32_e32 v212, v212, v139
	v_exp_f32_e32 v156, v156
	v_exp_f32_e32 v140, v140
	v_mfma_f32_32x32x16_bf16 v[34:49], v[202:205], v[226:229], v[34:49]
	v_xad_u32 v202, v246, 32, v1
	ds_read_b128 v[202:205], v202 offset:8192
	v_exp_f32_e32 v157, v157
	v_exp_f32_e32 v141, v141
	v_add_f32_e32 v213, v213, v156
	v_add_f32_e32 v212, v212, v140
	v_add_f32_e32 v213, v213, v157
	s_waitcnt lgkmcnt(4)
	v_mfma_f32_32x32x16_bf16 v[82:97], v[208:211], v[222:225], v[82:97]
	v_add_f32_e32 v212, v212, v141
	v_exp_f32_e32 v158, v158
	v_exp_f32_e32 v142, v142
	v_exp_f32_e32 v159, v159
	v_exp_f32_e32 v143, v143
	v_mfma_f32_32x32x16_bf16 v[18:33], v[208:211], v[226:229], v[18:33]
	v_xad_u32 v208, v246, 64, v1
	ds_read_b128 v[208:211], v208 offset:8192
	v_add_f32_e32 v213, v213, v158
	v_add_f32_e32 v212, v212, v142
	v_add_f32_e32 v213, v213, v159
	v_add_f32_e32 v212, v212, v143
	s_waitcnt lgkmcnt(3)
	v_mfma_f32_32x32x16_bf16 v[66:81], v[230:233], v[222:225], v[66:81]
	v_exp_f32_e32 v160, v160
	v_exp_f32_e32 v144, v144
	v_exp_f32_e32 v161, v161
	v_exp_f32_e32 v145, v145
	v_mfma_f32_32x32x16_bf16 v[2:17], v[230:233], v[226:229], v[2:17]
	v_xad_u32 v230, v246, s47, v1
	ds_read_b128 v[230:233], v230 offset:8192
	v_add_f32_e32 v213, v213, v160
	v_add_f32_e32 v212, v212, v144
	v_add_f32_e32 v213, v213, v161
	v_add_f32_e32 v212, v212, v145
	v_cvt_pk_bf16_f32 v222, v154, v155
	v_cvt_pk_bf16_f32 v226, v138, v139
	v_cvt_pk_bf16_f32 v223, v156, v157
	v_cvt_pk_bf16_f32 v227, v140, v141
	v_cvt_pk_bf16_f32 v224, v158, v159
	v_cvt_pk_bf16_f32 v228, v142, v143
	v_cvt_pk_bf16_f32 v225, v160, v161
	v_cvt_pk_bf16_f32 v229, v144, v145
	s_add_i32 s29, s29, 1
	s_branch .Lfb_loop
.Lfb_last0:
	s_waitcnt lgkmcnt(6)
	v_mfma_f32_32x32x16_bf16 v[114:129], v[198:201], v[222:225], v[114:129]
	v_add_f32_e32 v213, v213, v153
	v_add_f32_e32 v212, v212, v137
	v_cvt_pk_bf16_f32 v214, v146, v147
	v_cvt_pk_bf16_f32 v218, v130, v131
	v_cvt_pk_bf16_f32 v215, v148, v149
	v_cvt_pk_bf16_f32 v219, v132, v133
	v_cvt_pk_bf16_f32 v216, v150, v151
	v_cvt_pk_bf16_f32 v220, v134, v135
	v_cvt_pk_bf16_f32 v217, v152, v153
	v_cvt_pk_bf16_f32 v221, v136, v137
	v_mfma_f32_32x32x16_bf16 v[50:65], v[198:201], v[226:229], v[50:65]
	ds_read_b64_tr_b16 v[198:199], v234 offset:24576
	ds_read_b64_tr_b16 v[200:201], v235 offset:24576
	v_exp_f32_e32 v154, v154
	v_exp_f32_e32 v138, v138
	v_exp_f32_e32 v155, v155
	v_exp_f32_e32 v139, v139
	v_add_f32_e32 v213, v213, v154
	s_waitcnt lgkmcnt(6)
	v_mfma_f32_32x32x16_bf16 v[98:113], v[202:205], v[222:225], v[98:113]
	v_add_f32_e32 v212, v212, v138
	v_add_f32_e32 v213, v213, v155
	v_add_f32_e32 v212, v212, v139
	v_exp_f32_e32 v156, v156
	v_exp_f32_e32 v140, v140
	v_mfma_f32_32x32x16_bf16 v[34:49], v[202:205], v[226:229], v[34:49]
	ds_read_b64_tr_b16 v[202:203], v237 offset:24576
	ds_read_b64_tr_b16 v[204:205], v236 offset:24576
	v_exp_f32_e32 v157, v157
	v_exp_f32_e32 v141, v141
	v_add_f32_e32 v213, v213, v156
	v_add_f32_e32 v212, v212, v140
	v_add_f32_e32 v213, v213, v157
	s_waitcnt lgkmcnt(6)
	v_mfma_f32_32x32x16_bf16 v[82:97], v[208:211], v[222:225], v[82:97]
	v_add_f32_e32 v212, v212, v141
	v_exp_f32_e32 v158, v158
	v_exp_f32_e32 v142, v142
	v_exp_f32_e32 v159, v159
	v_exp_f32_e32 v143, v143
	v_mfma_f32_32x32x16_bf16 v[18:33], v[208:211], v[226:229], v[18:33]
	ds_read_b64_tr_b16 v[208:209], v238 offset:24576
	ds_read_b64_tr_b16 v[210:211], v239 offset:24576
	v_add_f32_e32 v213, v213, v158
	v_add_f32_e32 v212, v212, v142
	v_add_f32_e32 v213, v213, v159
	v_add_f32_e32 v212, v212, v143
	s_waitcnt lgkmcnt(6)
	v_mfma_f32_32x32x16_bf16 v[66:81], v[230:233], v[222:225], v[66:81]
	v_exp_f32_e32 v160, v160
	v_exp_f32_e32 v144, v144
	v_exp_f32_e32 v161, v161
	v_exp_f32_e32 v145, v145
	v_mfma_f32_32x32x16_bf16 v[2:17], v[230:233], v[226:229], v[2:17]
	ds_read_b64_tr_b16 v[230:231], v250 offset:24576
	ds_read_b64_tr_b16 v[232:233], v251 offset:24576
	v_add_f32_e32 v213, v213, v160
	v_add_f32_e32 v212, v212, v144
	v_add_f32_e32 v213, v213, v161
	v_add_f32_e32 v212, v212, v145
	v_cvt_pk_bf16_f32 v222, v154, v155
	v_cvt_pk_bf16_f32 v226, v138, v139
	v_cvt_pk_bf16_f32 v223, v156, v157
	v_cvt_pk_bf16_f32 v227, v140, v141
	v_cvt_pk_bf16_f32 v224, v158, v159
	v_cvt_pk_bf16_f32 v228, v142, v143
	v_cvt_pk_bf16_f32 v225, v160, v161
	v_cvt_pk_bf16_f32 v229, v144, v145
	s_waitcnt lgkmcnt(6)
	v_mfma_f32_32x32x16_bf16 v[114:129], v[198:201], v[214:217], v[114:129]
	v_mfma_f32_32x32x16_bf16 v[50:65], v[198:201], v[218:221], v[50:65]
	ds_read_b64_tr_b16 v[198:199], v234 offset:28672
	ds_read_b64_tr_b16 v[200:201], v235 offset:28672
	s_waitcnt lgkmcnt(6)
	v_mfma_f32_32x32x16_bf16 v[98:113], v[202:205], v[214:217], v[98:113]
	v_mfma_f32_32x32x16_bf16 v[34:49], v[202:205], v[218:221], v[34:49]
	ds_read_b64_tr_b16 v[202:203], v237 offset:28672
	ds_read_b64_tr_b16 v[204:205], v236 offset:28672
	s_waitcnt lgkmcnt(6)
	v_mfma_f32_32x32x16_bf16 v[82:97], v[208:211], v[214:217], v[82:97]
	v_mfma_f32_32x32x16_bf16 v[18:33], v[208:211], v[218:221], v[18:33]
	ds_read_b64_tr_b16 v[208:209], v238 offset:28672
	ds_read_b64_tr_b16 v[210:211], v239 offset:28672
	s_waitcnt lgkmcnt(6)
	v_mfma_f32_32x32x16_bf16 v[66:81], v[230:233], v[214:217], v[66:81]
	v_mfma_f32_32x32x16_bf16 v[2:17], v[230:233], v[218:221], v[2:17]
	ds_read_b64_tr_b16 v[230:231], v250 offset:28672
	ds_read_b64_tr_b16 v[232:233], v251 offset:28672
	s_waitcnt lgkmcnt(6)
	v_mfma_f32_32x32x16_bf16 v[114:129], v[198:201], v[222:225], v[114:129]
	v_mfma_f32_32x32x16_bf16 v[50:65], v[198:201], v[226:229], v[50:65]
	s_waitcnt lgkmcnt(4)
	v_mfma_f32_32x32x16_bf16 v[98:113], v[202:205], v[222:225], v[98:113]
	v_mfma_f32_32x32x16_bf16 v[34:49], v[202:205], v[226:229], v[34:49]
	s_waitcnt lgkmcnt(2)
	v_mfma_f32_32x32x16_bf16 v[82:97], v[208:211], v[222:225], v[82:97]
	v_mfma_f32_32x32x16_bf16 v[18:33], v[208:211], v[226:229], v[18:33]
	s_waitcnt lgkmcnt(0)
	v_mfma_f32_32x32x16_bf16 v[66:81], v[230:233], v[222:225], v[66:81]
	v_mfma_f32_32x32x16_bf16 v[2:17], v[230:233], v[226:229], v[2:17]
